# plus attention: s_setprio 1 over each straight-line MFMA cluster (QK and PV), 0 after
# baseline (speedup 1.0000x reference)
.LBB0_260:
	v_sub_f32_e32 v51, v96, v48
	v_exp_f32_e32 v51, v51
	v_sub_f32_e32 v55, v69, v48
	v_exp_f32_e32 v55, v55
	v_sub_f32_e32 v57, v65, v48
	v_exp_f32_e32 v57, v57
	v_sub_f32_e32 v50, v50, v48
	v_exp_f32_e32 v50, v50
	v_sub_f32_e32 v15, v15, v48
	v_add_f32_e32 v52, 0, v51
	v_exp_f32_e32 v15, v15
	v_sub_f32_e32 v14, v14, v48
	v_add_f32_e32 v52, v55, v52
	v_exp_f32_e32 v14, v14
	v_sub_f32_e32 v13, v13, v48
	v_add_f32_e32 v52, v57, v52
	v_exp_f32_e32 v13, v13
	v_sub_f32_e32 v12, v12, v48
	v_add_f32_e32 v52, v50, v52
	v_exp_f32_e32 v12, v12
	v_sub_f32_e32 v11, v11, v48
	v_add_f32_e32 v52, v15, v52
	v_exp_f32_e32 v59, v11
	v_sub_f32_e32 v10, v10, v48
	v_add_f32_e32 v52, v14, v52
	v_exp_f32_e32 v60, v10
	v_sub_f32_e32 v9, v9, v48
	v_add_f32_e32 v52, v13, v52
	v_exp_f32_e32 v61, v9
	v_sub_f32_e32 v8, v8, v48
	v_sub_f32_e32 v53, v70, v48
	v_add_f32_e32 v52, v12, v52
	v_exp_f32_e32 v62, v8
	v_sub_f32_e32 v7, v7, v48
	v_exp_f32_e32 v54, v53
	v_sub_f32_e32 v56, v68, v48
	v_add_f32_e32 v11, v59, v52
	v_exp_f32_e32 v63, v7
	v_sub_f32_e32 v6, v6, v48
	v_exp_f32_e32 v56, v56
	v_sub_f32_e32 v58, v64, v48
	v_add_f32_e32 v10, v60, v11
	v_exp_f32_e32 v64, v6
	v_sub_f32_e32 v5, v5, v48
	v_exp_f32_e32 v58, v58
	v_sub_f32_e32 v49, v49, v48
	v_add_f32_e32 v9, v61, v10
	v_exp_f32_e32 v65, v5
	v_sub_f32_e32 v4, v4, v48
	v_exp_f32_e32 v49, v49
	v_add_f32_e32 v8, v62, v9
	v_exp_f32_e32 v66, v4
	v_add_f32_e32 v53, 0, v54
	v_add_f32_e32 v7, v63, v8
	v_add_f32_e32 v53, v56, v53
	v_add_f32_e32 v6, v64, v7
	v_add_f32_e32 v53, v58, v53
	v_add_f32_e32 v5, v65, v6
	v_add_f32_e32 v53, v49, v53
	v_add_f32_e32 v4, v66, v5
	v_add_f32_e32 v67, v53, v4
	v_fmac_f32_e32 v67, v177, v0
	v_add_u32_e32 v0, v185, v184
	ds_read2st64_b64 v[8:11], v0 offset1:8
	v_add_u32_e32 v0, v185, v182
	v_cvt_pkrtz_f16_f32 v6, v15, v14
	v_cvt_pkrtz_f16_f32 v7, v13, v12
	ds_read2st64_b64 v[12:15], v0 offset1:8
	v_cvt_pkrtz_f16_f32 v4, v51, v55
	v_cvt_pkrtz_f16_f32 v5, v57, v50
	s_waitcnt lgkmcnt(0)
	v_mov_b32_e32 v50, v8
	v_mov_b32_e32 v51, v9
	v_mov_b32_e32 v52, v12
	v_mov_b32_e32 v53, v13
	v_mov_b32_e32 v12, v10
	v_mov_b32_e32 v13, v11
	v_add_u32_e32 v0, v185, v2
	ds_read2st64_b64 v[8:11], v0 offset1:8
	v_add_u32_e32 v0, v185, v1
	s_setprio 1
	v_mfma_f32_32x32x16_f16 v[32:47], v[12:15], v[4:7], v[32:47]
	ds_read2st64_b64 v[12:15], v0 offset1:8
	v_cvt_pkrtz_f16_f32 v0, v54, v56
	v_cvt_pkrtz_f16_f32 v1, v58, v49
	v_mov_b32_e32 v2, v3
	v_mov_b32_e32 v177, v67
	v_mfma_f32_32x32x16_f16 v[16:31], v[50:53], v[4:7], v[16:31]
	s_waitcnt lgkmcnt(0)
	v_mov_b32_e32 v50, v8
	v_mov_b32_e32 v51, v9
	v_mov_b32_e32 v52, v12
	v_mov_b32_e32 v53, v13
	v_mov_b32_e32 v12, v10
	v_mov_b32_e32 v13, v11
	v_cvt_pkrtz_f16_f32 v4, v59, v60
	v_cvt_pkrtz_f16_f32 v5, v61, v62
	v_cvt_pkrtz_f16_f32 v6, v63, v64
	v_cvt_pkrtz_f16_f32 v7, v65, v66
	v_add_u32_e32 v8, v185, v178
	ds_read2st64_b64 v[8:11], v8 offset0:16 offset1:24
	v_mfma_f32_32x32x16_f16 v[16:31], v[50:53], v[4:7], v[16:31]
	v_mfma_f32_32x32x16_f16 v[32:47], v[12:15], v[4:7], v[32:47]
	v_add_u32_e32 v4, v185, v179
	ds_read2st64_b64 v[4:7], v4 offset1:8
	s_waitcnt lgkmcnt(0)
	v_mov_b32_e32 v14, v8
	v_mov_b32_e32 v15, v9
	v_mov_b32_e32 v12, v4
	v_mov_b32_e32 v13, v5
	v_mov_b32_e32 v8, v6
	v_mov_b32_e32 v9, v7
	v_mfma_f32_32x32x16_f16 v[16:31], v[12:15], v[0:3], v[16:31]
	s_nop 0
	v_mfma_f32_32x32x16_f16 v[32:47], v[8:11], v[0:3], v[32:47]
	s_setprio 0

.LBB0_291:
	s_or_b64 exec, exec, s[36:37]
	s_mul_hi_u32 s36, s54, 0xaaaaaaab
	s_lshr_b32 s36, s36, 2
	s_mul_i32 s36, s36, 0x18000
	v_subrev_u32_e32 v178, s36, v164
	v_subrev_u32_e32 v179, s36, v166
	v_subrev_u32_e32 v1, s36, v168
	v_subrev_u32_e32 v2, s36, v169
	v_subrev_u32_e32 v182, s36, v170
	v_subrev_u32_e32 v184, s36, v172
	v_subrev_u32_e32 v180, s36, v173
	v_subrev_u32_e32 v181, s36, v175
	v_subrev_u32_e32 v0, s36, v129
	v_subrev_u32_e32 v6, s36, v128
	v_subrev_u32_e32 v8, s36, v115
	v_subrev_u32_e32 v7, s36, v127
	s_barrier
	v_cmp_ge_i32_e32 vcc, s54, v123
	s_or_b64 s[36:37], s[48:49], vcc
	s_and_saveexec_b64 s[44:45], s[36:37]
	s_xor_b64 s[36:37], exec, s[44:45]
	s_cbranch_execz .LBB0_295
	v_add_u32_e32 v5, s53, v163
	v_add_u32_e32 v4, v5, v8
	ds_read_b128 v[8:11], v4
	v_add_u32_e32 v0, v5, v0
	s_waitcnt lgkmcnt(0)
	s_setprio 1
	v_mfma_f32_32x32x16_f16 v[48:63], v[8:11], v[88:91], 0
	ds_read_b128 v[8:11], v4 offset:4096
	v_add_u32_e32 v4, v5, v7
	s_waitcnt lgkmcnt(0)
	v_mfma_f32_32x32x16_f16 v[64:79], v[8:11], v[88:91], 0
	ds_read_b128 v[8:11], v4
	s_waitcnt lgkmcnt(0)
	v_mfma_f32_32x32x16_f16 v[48:63], v[8:11], v[80:83], v[48:63]
	ds_read_b128 v[8:11], v4 offset:4096
	v_add_u32_e32 v4, v5, v6
	s_waitcnt lgkmcnt(0)
	v_mfma_f32_32x32x16_f16 v[64:79], v[8:11], v[80:83], v[64:79]
	ds_read_b128 v[6:9], v4
	s_waitcnt lgkmcnt(0)
	v_mfma_f32_32x32x16_f16 v[48:63], v[6:9], v[84:87], v[48:63]
	ds_read_b128 v[6:9], v4 offset:4096
	s_waitcnt lgkmcnt(0)
	v_mfma_f32_32x32x16_f16 v[64:79], v[6:9], v[84:87], v[64:79]
	ds_read_b128 v[6:9], v0
	s_waitcnt lgkmcnt(0)
	v_mfma_f32_32x32x16_f16 v[48:63], v[6:9], v[92:95], v[48:63]
	ds_read_b128 v[6:9], v0 offset:4096
	s_waitcnt lgkmcnt(0)
	v_mfma_f32_32x32x16_f16 v[64:79], v[6:9], v[92:95], v[64:79]
	s_setprio 0
	s_nop 11
	v_max3_f32 v0, v48, s55, v64
	v_max3_f32 v0, v0, v49, v65
	v_max3_f32 v0, v0, v50, v66
	v_max3_f32 v0, v0, v51, v67
	v_max3_f32 v0, v0, v52, v68
	v_max3_f32 v0, v0, v53, v69
	v_max3_f32 v0, v0, v54, v70
	v_max3_f32 v0, v0, v55, v71
	v_max3_f32 v0, v0, v56, v72
	v_max3_f32 v0, v0, v57, v73
	v_max3_f32 v0, v0, v58, v74
	v_max3_f32 v0, v0, v59, v75
	v_max3_f32 v0, v0, v60, v76
	v_max3_f32 v0, v0, v61, v77
	v_max3_f32 v0, v0, v62, v78
	v_max3_f32 v0, v0, v63, v79
	v_mov_b32_e32 v4, v0
	s_nop 1
	v_permlane32_swap_b32_e32 v0, v4
	v_max3_f32 v4, v186, v0, v4
	v_sub_f32_e32 v0, v186, v4
	v_exp_f32_e32 v0, v0
	s_nop 0
	v_cmp_neq_f32_e32 vcc, 1.0, v0
	s_cbranch_vccz .LBB0_294
	v_pk_mul_f32 v[30:31], v[30:31], v[0:1] op_sel_hi:[1,0]
	v_pk_mul_f32 v[28:29], v[28:29], v[0:1] op_sel_hi:[1,0]
	v_pk_mul_f32 v[26:27], v[26:27], v[0:1] op_sel_hi:[1,0]
	v_pk_mul_f32 v[24:25], v[24:25], v[0:1] op_sel_hi:[1,0]
	v_pk_mul_f32 v[22:23], v[22:23], v[0:1] op_sel_hi:[1,0]
	v_pk_mul_f32 v[20:21], v[20:21], v[0:1] op_sel_hi:[1,0]
	v_pk_mul_f32 v[18:19], v[18:19], v[0:1] op_sel_hi:[1,0]
	v_pk_mul_f32 v[16:17], v[16:17], v[0:1] op_sel_hi:[1,0]
	v_pk_mul_f32 v[46:47], v[46:47], v[0:1] op_sel_hi:[1,0]
	v_pk_mul_f32 v[44:45], v[44:45], v[0:1] op_sel_hi:[1,0]
	v_pk_mul_f32 v[42:43], v[42:43], v[0:1] op_sel_hi:[1,0]
	v_pk_mul_f32 v[40:41], v[40:41], v[0:1] op_sel_hi:[1,0]
	v_pk_mul_f32 v[38:39], v[38:39], v[0:1] op_sel_hi:[1,0]
	v_pk_mul_f32 v[36:37], v[36:37], v[0:1] op_sel_hi:[1,0]
	v_pk_mul_f32 v[34:35], v[34:35], v[0:1] op_sel_hi:[1,0]
	v_pk_mul_f32 v[32:33], v[32:33], v[0:1] op_sel_hi:[1,0]
.LBB0_294:
	v_sub_f32_e32 v10, v65, v4
	v_exp_f32_e32 v15, v10
	v_sub_f32_e32 v10, v50, v4
	v_sub_f32_e32 v50, v71, v4
	v_sub_f32_e32 v6, v48, v4
	v_sub_f32_e32 v8, v64, v4
	v_sub_f32_e32 v48, v69, v4
	v_exp_f32_e32 v69, v50
	v_sub_f32_e32 v50, v56, v4
	v_exp_f32_e32 v6, v6
	v_exp_f32_e32 v14, v8
	v_sub_f32_e32 v9, v49, v4
	v_exp_f32_e32 v56, v50
	v_sub_f32_e32 v50, v72, v4
	v_exp_f32_e32 v9, v9
	v_sub_f32_e32 v11, v66, v4
	v_sub_f32_e32 v49, v70, v4
	v_exp_f32_e32 v70, v50
	v_sub_f32_e32 v50, v57, v4
	v_exp_f32_e32 v10, v10
	v_exp_f32_e32 v64, v11
	v_sub_f32_e32 v11, v51, v4
	v_sub_f32_e32 v12, v67, v4
	v_exp_f32_e32 v57, v50
	v_sub_f32_e32 v50, v73, v4
	v_exp_f32_e32 v11, v11
	v_exp_f32_e32 v65, v12
	v_sub_f32_e32 v12, v52, v4
	v_sub_f32_e32 v13, v68, v4
	v_exp_f32_e32 v71, v50
	v_sub_f32_e32 v50, v58, v4
	v_add_f32_e32 v7, 0, v6
	v_add_f32_e32 v8, 0, v14
	v_exp_f32_e32 v12, v12
	v_exp_f32_e32 v66, v13
	v_sub_f32_e32 v13, v53, v4
	v_exp_f32_e32 v58, v50
	v_sub_f32_e32 v50, v74, v4
	v_add_f32_e32 v7, v9, v7
	v_add_f32_e32 v8, v15, v8
	v_exp_f32_e32 v13, v13
	v_exp_f32_e32 v67, v48
	v_sub_f32_e32 v48, v54, v4
	v_exp_f32_e32 v72, v50
	v_sub_f32_e32 v50, v59, v4
	v_add_f32_e32 v7, v10, v7
	v_add_f32_e32 v8, v64, v8
	v_exp_f32_e32 v48, v48
	v_exp_f32_e32 v68, v49
	v_sub_f32_e32 v49, v55, v4
	v_exp_f32_e32 v73, v50
	v_sub_f32_e32 v50, v75, v4
	v_add_f32_e32 v7, v11, v7
	v_add_f32_e32 v8, v65, v8
	v_exp_f32_e32 v49, v49
	v_exp_f32_e32 v74, v50
	v_sub_f32_e32 v50, v60, v4
	v_add_f32_e32 v7, v12, v7
	v_add_f32_e32 v8, v66, v8
	v_exp_f32_e32 v60, v50
	v_sub_f32_e32 v50, v76, v4
	v_add_f32_e32 v7, v13, v7
	v_add_f32_e32 v8, v67, v8
	v_exp_f32_e32 v75, v50
	v_sub_f32_e32 v50, v61, v4
	v_add_f32_e32 v7, v48, v7
	v_add_f32_e32 v8, v68, v8
	v_exp_f32_e32 v61, v50
	v_sub_f32_e32 v50, v77, v4
	v_add_f32_e32 v7, v49, v7
	v_add_f32_e32 v8, v69, v8
	v_exp_f32_e32 v76, v50
	v_sub_f32_e32 v50, v62, v4
	v_add_f32_e32 v7, v56, v7
	v_add_f32_e32 v8, v70, v8
	v_exp_f32_e32 v62, v50
	v_sub_f32_e32 v50, v78, v4
	v_add_f32_e32 v7, v57, v7
	v_add_f32_e32 v8, v71, v8
	v_exp_f32_e32 v77, v50
	v_sub_f32_e32 v50, v63, v4
	v_add_f32_e32 v7, v58, v7
	v_add_f32_e32 v8, v72, v8
	v_exp_f32_e32 v63, v50
	v_sub_f32_e32 v50, v79, v4
	v_add_f32_e32 v7, v73, v7
	v_add_f32_e32 v8, v74, v8
	v_exp_f32_e32 v78, v50
	v_add_f32_e32 v7, v60, v7
	v_add_f32_e32 v8, v75, v8
	v_add_f32_e32 v7, v61, v7
	v_add_f32_e32 v8, v76, v8
	v_add_f32_e32 v7, v62, v7
	v_add_f32_e32 v8, v77, v8
	v_add_f32_e32 v7, v63, v7
	v_add_f32_e32 v8, v78, v8
	v_add_f32_e32 v59, v8, v7
	v_fmac_f32_e32 v59, v177, v0
	v_cvt_pkrtz_f16_f32 v7, v10, v11
	v_cvt_pkrtz_f16_f32 v8, v12, v13
	v_cvt_pkrtz_f16_f32 v6, v6, v9
	v_cvt_pkrtz_f16_f32 v9, v48, v49
	v_add_u32_e32 v0, v5, v184
	v_add_u32_e32 v196, v5, v182
	ds_read_b64 v[52:53], v0
	ds_read_b64 v[48:49], v0 offset:4096
	ds_read_b64 v[54:55], v196
	ds_read_b64 v[50:51], v196 offset:4096
	v_add_u32_e32 v0, v5, v2
	v_add_u32_e32 v196, v5, v1
	ds_read_b64 v[192:193], v0
	ds_read_b64 v[188:189], v0 offset:4096
	ds_read_b64 v[194:195], v196
	ds_read_b64 v[190:191], v196 offset:4096
	v_cvt_pkrtz_f16_f32 v10, v56, v57
	v_cvt_pkrtz_f16_f32 v11, v58, v73
	v_cvt_pkrtz_f16_f32 v12, v60, v61
	v_cvt_pkrtz_f16_f32 v13, v62, v63
	s_waitcnt lgkmcnt(4)
	s_setprio 1
	v_mfma_f32_32x32x16_f16 v[32:47], v[48:51], v[6:9], v[32:47]
	v_mfma_f32_32x32x16_f16 v[16:31], v[52:55], v[6:9], v[16:31]
	v_add_u32_e32 v0, v5, v179
	v_add_u32_e32 v196, v5, v178
	ds_read_b64 v[52:53], v0
	ds_read_b64 v[48:49], v0 offset:4096
	ds_read_b64 v[54:55], v196 offset:8192
	ds_read_b64 v[50:51], v196 offset:12288
	v_cvt_pkrtz_f16_f32 v6, v14, v15
	v_cvt_pkrtz_f16_f32 v7, v64, v65
	v_cvt_pkrtz_f16_f32 v8, v66, v67
	v_cvt_pkrtz_f16_f32 v9, v68, v69
	s_waitcnt lgkmcnt(4)
	v_mfma_f32_32x32x16_f16 v[32:47], v[188:191], v[10:13], v[32:47]
	v_mfma_f32_32x32x16_f16 v[16:31], v[192:195], v[10:13], v[16:31]
	v_add_u32_e32 v0, v5, v181
	v_add_u32_e32 v196, v5, v180
	ds_read_b64 v[192:193], v0
	ds_read_b64 v[188:189], v0 offset:4096
	ds_read_b64 v[194:195], v196
	ds_read_b64 v[190:191], v196 offset:4096
	v_cvt_pkrtz_f16_f32 v13, v77, v78
	v_cvt_pkrtz_f16_f32 v10, v70, v71
	v_cvt_pkrtz_f16_f32 v11, v72, v74
	v_cvt_pkrtz_f16_f32 v12, v75, v76
	s_waitcnt lgkmcnt(4)
	v_mfma_f32_32x32x16_f16 v[32:47], v[48:51], v[6:9], v[32:47]
	v_mfma_f32_32x32x16_f16 v[16:31], v[52:55], v[6:9], v[16:31]
	s_waitcnt lgkmcnt(0)
	v_mfma_f32_32x32x16_f16 v[32:47], v[188:191], v[10:13], v[32:47]
	v_mfma_f32_32x32x16_f16 v[16:31], v[192:195], v[10:13], v[16:31]
	s_setprio 0
.LBB0_295:
	s_andn2_saveexec_b64 s[36:37], s[36:37]
	s_cbranch_execz .LBB0_263
	v_add_u32_e32 v4, s54, v120
	v_cmp_ge_u32_e32 vcc, v4, v122
	v_cmp_le_u32_e64 s[44:45], v4, v130
	s_and_b64 s[50:51], vcc, s[44:45]
	s_and_saveexec_b64 s[44:45], s[50:51]
	s_cbranch_execz .LBB0_262
	v_add_u32_e32 v185, s53, v163
	v_add_u32_e32 v4, v185, v8
	ds_read_b128 v[64:67], v4
	ds_read_b128 v[68:71], v4 offset:4096
	v_add_u32_e32 v4, v185, v7
	ds_read_b128 v[96:99], v4
	ds_read_b128 v[104:107], v4 offset:4096
	v_add_u32_e32 v4, v185, v6
	v_add_u32_e32 v0, v185, v0
	ds_read_b128 v[12:15], v4
	ds_read_b128 v[100:103], v4 offset:4096
	ds_read_b128 v[4:7], v0
	ds_read_b128 v[8:11], v0 offset:4096
	v_add_u32_e32 v193, 16, v149
	v_add_u32_e32 v190, 16, v147
	v_add_u32_e32 v191, 16, v145
	v_add_u32_e32 v192, 16, v143
	v_add_u32_e32 v189, 16, v134
	v_add_u32_e32 v188, 16, v133
	v_add_u32_e32 v187, 16, v132
	v_add_u32_e32 v0, 16, v131
	s_and_saveexec_b64 s[50:51], s[42:43]
	s_xor_b64 s[50:51], exec, s[50:51]
	s_cbranch_execz .LBB0_301
	s_waitcnt lgkmcnt(0)
	s_setprio 1
	v_mfma_f32_32x32x16_f16 v[48:63], v[68:71], v[88:91], 0
	v_add_u32_e32 v68, 16, v154
	v_add_u32_e32 v69, 16, v153
	v_add_u32_e32 v70, 16, v152
	v_add_u32_e32 v71, 16, v151
	v_mfma_f32_32x32x16_f16 v[48:63], v[104:107], v[80:83], v[48:63]
	v_add_u32_e32 v106, 16, v156
	v_add_u32_e32 v107, 16, v155
	v_mfma_f32_32x32x16_f16 v[48:63], v[100:103], v[84:87], v[48:63]
	v_add_u32_e32 v101, 16, v162
	v_mfma_f32_32x32x16_f16 v[48:63], v[8:11], v[92:95], v[48:63]
	ds_read_b32 v8, v193
	ds_read_b32 v9, v190
	ds_read_b32 v11, v191
	ds_read_b32 v72, v192
	ds_read_b32 v102, v68
	ds_read_b32 v103, v69
	ds_read_b32 v104, v70
	ds_read_b32 v105, v71
	s_waitcnt lgkmcnt(0)
	s_nop 2
	v_add_f32_e32 v100, v48, v8
	v_add_f32_e32 v8, v51, v72
	v_mfma_f32_32x32x16_f16 v[64:79], v[64:67], v[88:91], 0
	v_add_f32_e32 v10, v49, v9
	v_add_f32_e32 v9, v50, v11
	v_add_u32_e32 v11, 16, v161
	v_add_u32_e32 v48, 16, v160
	v_add_u32_e32 v49, 16, v159
	v_add_u32_e32 v50, 16, v158
	v_add_u32_e32 v51, 16, v157
	v_mfma_f32_32x32x16_f16 v[64:79], v[96:99], v[80:83], v[64:79]
	s_setprio 0
	ds_read_b32 v96, v101
	ds_read_b32 v11, v11
	ds_read_b32 v48, v48
	ds_read_b32 v49, v49
	ds_read_b32 v50, v50
	ds_read_b32 v98, v51
	ds_read_b32 v99, v106
	ds_read_b32 v101, v107
	s_waitcnt lgkmcnt(0)
	v_add_f32_e32 v97, v52, v96
	v_add_f32_e32 v96, v53, v11
	v_add_f32_e32 v53, v54, v48
	v_add_f32_e32 v52, v55, v49
	v_add_f32_e32 v51, v56, v50
	v_add_f32_e32 v50, v57, v98
	v_mfma_f32_32x32x16_f16 v[64:79], v[12:15], v[84:87], v[64:79]
	ds_read_b32 v11, v189
	ds_read_b32 v12, v188
	ds_read_b32 v48, v187
	ds_read_b32 v0, v0
	v_add_f32_e32 v15, v58, v99
	v_add_f32_e32 v14, v59, v101
	v_add_f32_e32 v13, v60, v102
	v_mfma_f32_32x32x16_f16 v[64:79], v[4:7], v[92:95], v[64:79]
	v_add_f32_e32 v6, v62, v104
	v_add_f32_e32 v4, v63, v105
	s_waitcnt lgkmcnt(0)
	s_nop 8
	v_add_f32_e32 v5, v79, v0
	v_max3_f32 v0, v100, s55, v10
	v_max3_f32 v0, v0, v9, v8
	v_max3_f32 v0, v0, v97, v96
	v_max3_f32 v0, v0, v53, v52
	v_max3_f32 v0, v0, v51, v50
	v_add_f32_e32 v49, v76, v11
	v_max3_f32 v0, v0, v15, v14
	v_add_f32_e32 v12, v77, v12
	v_add_f32_e32 v11, v61, v103
	v_max3_f32 v0, v0, v49, v13
	v_add_f32_e32 v7, v78, v48
	v_max3_f32 v0, v0, v12, v11
	v_max3_f32 v0, v0, v7, v6
	v_max3_f32 v0, v0, v5, v4
	v_mov_b32_e32 v48, v0
	s_nop 1
	v_permlane32_swap_b32_e32 v0, v48
	v_max3_f32 v48, v186, v0, v48
	v_sub_f32_e32 v0, v186, v48
	v_exp_f32_e32 v0, v0
	s_nop 0
	v_cmp_neq_f32_e32 vcc, 1.0, v0
	s_cbranch_vccz .LBB0_300
	v_pk_mul_f32 v[30:31], v[30:31], v[0:1] op_sel_hi:[1,0]
	v_pk_mul_f32 v[28:29], v[28:29], v[0:1] op_sel_hi:[1,0]
	v_pk_mul_f32 v[26:27], v[26:27], v[0:1] op_sel_hi:[1,0]
	v_pk_mul_f32 v[24:25], v[24:25], v[0:1] op_sel_hi:[1,0]
	v_pk_mul_f32 v[22:23], v[22:23], v[0:1] op_sel_hi:[1,0]
	v_pk_mul_f32 v[20:21], v[20:21], v[0:1] op_sel_hi:[1,0]
	v_pk_mul_f32 v[18:19], v[18:19], v[0:1] op_sel_hi:[1,0]
	v_pk_mul_f32 v[16:17], v[16:17], v[0:1] op_sel_hi:[1,0]
	v_pk_mul_f32 v[46:47], v[46:47], v[0:1] op_sel_hi:[1,0]
	v_pk_mul_f32 v[44:45], v[44:45], v[0:1] op_sel_hi:[1,0]
	v_pk_mul_f32 v[42:43], v[42:43], v[0:1] op_sel_hi:[1,0]
	v_pk_mul_f32 v[40:41], v[40:41], v[0:1] op_sel_hi:[1,0]
	v_pk_mul_f32 v[38:39], v[38:39], v[0:1] op_sel_hi:[1,0]
	v_pk_mul_f32 v[36:37], v[36:37], v[0:1] op_sel_hi:[1,0]
	v_pk_mul_f32 v[34:35], v[34:35], v[0:1] op_sel_hi:[1,0]
	v_pk_mul_f32 v[32:33], v[32:33], v[0:1] op_sel_hi:[1,0]

.LBB0_301:
	s_andn2_saveexec_b64 s[50:51], s[50:51]
	s_cbranch_execz .LBB0_261
	s_waitcnt lgkmcnt(0)
	s_setprio 1
	v_mfma_f32_32x32x16_f16 v[48:63], v[64:67], v[88:91], 0
	v_mfma_f32_32x32x16_f16 v[64:79], v[68:71], v[88:91], 0
	v_mfma_f32_32x32x16_f16 v[48:63], v[96:99], v[80:83], v[48:63]
	v_add_u32_e32 v96, 16, v150
	v_add_u32_e32 v97, 16, v141
	v_add_u32_e32 v98, 16, v140
	v_add_u32_e32 v99, 16, v139
	v_mfma_f32_32x32x16_f16 v[64:79], v[104:107], v[80:83], v[64:79]
	v_mfma_f32_32x32x16_f16 v[48:63], v[12:15], v[84:87], v[48:63]
	v_add_u32_e32 v12, 16, v148
	v_add_u32_e32 v13, 16, v146
	v_add_u32_e32 v14, 16, v144
	v_add_u32_e32 v15, 16, v142
	v_mfma_f32_32x32x16_f16 v[64:79], v[100:103], v[84:87], v[64:79]
	v_mfma_f32_32x32x16_f16 v[48:63], v[4:7], v[92:95], v[48:63]
	ds_read_b32 v4, v96
	ds_read_b32 v5, v12
	ds_read_b32 v6, v13
	ds_read_b32 v7, v14
	ds_read_b32 v12, v15
	ds_read_b32 v13, v97
	ds_read_b32 v97, v98
	ds_read_b32 v98, v99
	v_add_u32_e32 v14, 16, v137
	v_add_u32_e32 v15, 16, v136
	s_waitcnt lgkmcnt(0)
	s_nop 0
	v_add_f32_e32 v96, v48, v4
	v_mfma_f32_32x32x16_f16 v[64:79], v[8:11], v[92:95], v[64:79]
	s_setprio 0
	v_add_u32_e32 v4, 16, v138
	v_add_u32_e32 v48, 16, v135
	ds_read_b32 v99, v193
	ds_read_b32 v100, v190
	ds_read_b32 v101, v191
	ds_read_b32 v102, v192
	ds_read_b32 v4, v4
	ds_read_b32 v103, v14
	ds_read_b32 v104, v15
	ds_read_b32 v48, v48
	s_nop 1
	v_add_f32_e32 v69, v49, v5
	s_waitcnt lgkmcnt(0)
	v_add_f32_e32 v11, v56, v4
	v_add_f32_e32 v15, v52, v12
	v_add_f32_e32 v14, v53, v13
	v_add_f32_e32 v68, v65, v100
	v_add_f32_e32 v65, v50, v6
	v_add_f32_e32 v50, v51, v7
	ds_read_b32 v4, v189
	ds_read_b32 v5, v188
	ds_read_b32 v51, v187
	ds_read_b32 v0, v0
	v_add_f32_e32 v70, v64, v99
	s_waitcnt lgkmcnt(0)
	v_add_f32_e32 v7, v60, v4
	v_add_f32_e32 v64, v66, v101
	v_add_f32_e32 v49, v67, v102
	v_add_f32_e32 v4, v63, v0
	v_max3_f32 v0, v96, s55, v70
	v_max3_f32 v0, v0, v69, v68
	v_max3_f32 v0, v0, v65, v64
	v_max3_f32 v0, v0, v50, v49
	v_add_f32_e32 v13, v54, v97
	v_add_f32_e32 v12, v55, v98
	v_max3_f32 v0, v0, v15, v14
	v_add_f32_e32 v10, v57, v103
	v_max3_f32 v0, v0, v13, v12
	v_add_f32_e32 v9, v58, v104
	v_add_f32_e32 v8, v59, v48
	v_max3_f32 v0, v0, v11, v10
	v_add_f32_e32 v6, v61, v5
	v_max3_f32 v0, v0, v9, v8
	v_add_f32_e32 v5, v62, v51
	v_max3_f32 v0, v0, v7, v6
	v_max3_f32 v0, v0, v5, v4
	v_mov_b32_e32 v48, v0
	s_nop 1
	v_permlane32_swap_b32_e32 v0, v48
	v_max3_f32 v48, v186, v0, v48
	v_sub_f32_e32 v0, v186, v48
	v_exp_f32_e32 v0, v0
	s_nop 0
	v_cmp_neq_f32_e32 vcc, 1.0, v0
	s_cbranch_vccz .LBB0_260
	v_pk_mul_f32 v[30:31], v[30:31], v[0:1] op_sel_hi:[1,0]
	v_pk_mul_f32 v[28:29], v[28:29], v[0:1] op_sel_hi:[1,0]
	v_pk_mul_f32 v[26:27], v[26:27], v[0:1] op_sel_hi:[1,0]
	v_pk_mul_f32 v[24:25], v[24:25], v[0:1] op_sel_hi:[1,0]
	v_pk_mul_f32 v[22:23], v[22:23], v[0:1] op_sel_hi:[1,0]
	v_pk_mul_f32 v[20:21], v[20:21], v[0:1] op_sel_hi:[1,0]
	v_pk_mul_f32 v[18:19], v[18:19], v[0:1] op_sel_hi:[1,0]
	v_pk_mul_f32 v[16:17], v[16:17], v[0:1] op_sel_hi:[1,0]
	v_pk_mul_f32 v[46:47], v[46:47], v[0:1] op_sel_hi:[1,0]
	v_pk_mul_f32 v[44:45], v[44:45], v[0:1] op_sel_hi:[1,0]
	v_pk_mul_f32 v[42:43], v[42:43], v[0:1] op_sel_hi:[1,0]
	v_pk_mul_f32 v[40:41], v[40:41], v[0:1] op_sel_hi:[1,0]
	v_pk_mul_f32 v[38:39], v[38:39], v[0:1] op_sel_hi:[1,0]
	v_pk_mul_f32 v[36:37], v[36:37], v[0:1] op_sel_hi:[1,0]
	v_pk_mul_f32 v[34:35], v[34:35], v[0:1] op_sel_hi:[1,0]
	v_pk_mul_f32 v[32:33], v[32:33], v[0:1] op_sel_hi:[1,0]
	s_branch .LBB0_260
